# v66 + attention unit prologue: barrier waits only for the K/V LDS-DMA (vmcnt(12)), Q register loads complete later
# speedup vs baseline: 1.0013x; 1.0007x over previous
; __device__ __forceinline__ void attn_unit(const bf16_t* __restrict__ Qs, const bf16_t* __restrict__ Kn, const bf16_t* __restrict__ Kr, const bf16_t* __restrict__ Vs, bf16_t* Os, int q0, int Lp, char* lds, const int tid) {
;     const int wid = tid >> 6, lane = tid & 63, r32 = lane & 31, hi = lane >> 5; const int wu = __builtin_amdgcn_readfirstlane(wid);
;     char* V_lds = lds; char* K_lds = lds + 2 * SHM_V;
;     float* ws = (float*)(lds + 2 * SHM_V + 2 * SHM_K) + wid * 64; float* li_l = ws; float* al_l = ws + 32;
;     float m_reg = -1e30f, l_reg = 0; f32x16 o[4] = {}; bf16x8 qr[12 - NQL];
;     char* qslot = lds + SHM_QR + wid * (NQL * 1024) + lane * 16;
;     int kb[4];
; #pragma unroll
;     for (int c = 0; c < 4; ++c) kb[c] = KSWZ(r32, c * 32 + hi * 16);
;     const bf16_t* ksrc[3];
; #pragma unroll
;     for (int n = 0; n < 3; ++n) { const int p = (wid * 3 + n) * 64 + lane, row = p / 24, cp = p % 24, c = (cp & 24) | ((cp ^ row) & 7);
;         ksrc[n] = c < 16 ? Kn + (size_t)row * 2048 + c * 8 : Kr + (size_t)row * 64 + (c - 16) * 8; }
;     unsigned vsrc[2];
; #pragma unroll
;     for (int n = 0; n < 2; ++n) { const int p = (wid * 2 + n) * 64 + lane, sub = p >> 5, elt = (p & 31) * 8, kk = (sub >> 2) * 8 + (elt >> 5), k = (kk & ~0xC) | ((kk & 4) << 1) | ((kk & 8) >> 1), c = (sub & 3) * 32 + (elt & 31);
;         vsrc[n] = (unsigned)(k * 2048 + c) * 2u; }
;     const unsigned lK = (unsigned)(uintptr_t)K_lds + wu * 3072, lV = (unsigned)(uintptr_t)V_lds + wu * 2048;
;     bool krope[3];
; #pragma unroll
; __device__ __forceinline__ void attn_phase(const Frame& F, const bf16_t* Q, const bf16_t* KN, const bf16_t* KR, const bf16_t* V, bf16_t* O) {
;     ...
;         if (exact) { smp = i >= np; u = !smp ? (i < 8 ? c + 256 * i : 2048 + c) : (c < 64 ? c + 64 * (i - np) : 448 + (c - 64) + 192 * (i - np)); }
;         else { const int g = c + F.G * i; smp = g >= NUP; u = smp ? g - NUP : g; }
;         const int nqb = smp ? NQS : NQP, Lp = smp ? LP_S : LP_P;
;         const int qb = u % nqb, sh = u / nqb, head = sh % MH, seq = sh / MH; const size_t rb = (smp ? (size_t)ROWS0 : 0) + (size_t)seq * Lp;
;         attn_unit(Q + rb * 3072 + head * MQK, KN + rb * 2048 + head * MNOPE, KR + rb * 64, V + rb * 2048 + head * MV, O + rb * 2048 + head * MV, qb * 256, Lp, F.ldsg, F.tid);
.LBB0_621:
	s_and_b64 s[22:23], s[0:1], exec
	s_cselect_b32 s13, 17, 33
	v_cvt_f32_ubyte0_e32 v0, s13
	v_rcp_iflag_f32_e32 v0, v0
	s_movk_i32 s22, 0x2080
	s_cselect_b32 s62, 0x1080, s22
	s_sub_i32 s30, 0, s13
	v_mul_f32_e32 v0, 0x4f7ffffe, v0
	v_cvt_u32_f32_e32 v0, v0
	s_abs_i32 s23, s12
	s_ashr_i32 s22, s12, 31
	s_movk_i32 s64, 0xff00
	v_readfirstlane_b32 s31, v0
	s_mul_i32 s30, s30, s31
	s_mul_hi_u32 s30, s31, s30
	s_add_i32 s31, s31, s30
	s_mul_hi_u32 s30, s23, s31
	s_mul_i32 s31, s30, s13
	s_sub_i32 s23, s23, s31
	s_add_i32 s42, s30, 1
	s_sub_i32 s31, s23, s13
	s_cmp_ge_u32 s23, s13
	s_cselect_b32 s30, s42, s30
	s_cselect_b32 s23, s31, s23
	s_add_i32 s31, s30, 1
	s_cmp_ge_u32 s23, s13
	s_cselect_b32 s23, s31, s30
	s_xor_b32 s23, s23, s22
	s_sub_i32 s22, s23, s22
	s_mul_i32 s13, s22, s13
	s_sub_i32 s48, s12, s13
	s_ashr_i32 s12, s22, 31
	s_lshr_b32 s12, s12, 28
	s_add_i32 s12, s22, s12
	s_ashr_i32 s13, s12, 4
	s_and_b32 s12, s12, -16
	s_sub_i32 s46, s22, s12
	s_and_b64 s[0:1], s[0:1], exec
	s_cselect_b32 s0, 0x8200, 0
	s_mul_hi_i32 s1, s13, s62
	s_mul_i32 s13, s13, s62
	s_add_u32 s12, s13, s0
	s_addc_u32 s13, s1, 0
	s_mul_i32 s0, s13, 0x1800
	s_mul_hi_u32 s1, s12, 0x1800
	s_add_i32 s1, s1, s0
	s_mul_i32 s0, s12, 0x1800
	s_add_u32 s22, s52, s0
	s_mul_i32 s0, s46, 0xc0
	s_addc_u32 s23, s53, s1
	s_ashr_i32 s1, s0, 31
	s_lshl_b64 s[0:1], s[0:1], 1
	s_add_u32 s42, s22, s0
	s_addc_u32 s43, s23, s1
	s_lshl_b64 s[22:23], s[12:13], 11
	s_lshl_b64 s[30:31], s[12:13], 12
	s_add_u32 s47, s54, s30
	s_addc_u32 s49, s55, s31
	s_lshl_b32 s0, s46, 7
	s_ashr_i32 s1, s0, 31
	s_lshl_b64 s[0:1], s[0:1], 1
	s_add_u32 s46, s47, s0
	s_addc_u32 s47, s49, s1
	s_lshl_b64 s[12:13], s[12:13], 7
	s_add_u32 s12, s60, s12
	s_addc_u32 s13, s61, s13
	v_lshl_add_u64 v[2:3], s[12:13], 0, v[198:199]
	v_lshl_add_u64 v[0:1], s[46:47], 0, v[200:201]
	v_lshl_add_u64 v[2:3], v[2:3], 0, v[192:193]
	s_mov_b32 s65, -1
	v_lshl_add_u64 v[0:1], v[0:1], 0, v[192:193]
	v_lshl_add_u64 v[2:3], v[2:3], 0, s[64:65]
	s_add_u32 s30, s11, s30
	v_cndmask_b32_e64 v229, v3, v1, s[34:35]
	v_cndmask_b32_e64 v228, v2, v0, s[34:35]
	v_mov_b32_e32 v217, v193
	v_lshl_add_u64 v[2:3], s[12:13], 0, v[202:203]
	s_addc_u32 s31, s18, s31
	v_lshl_add_u64 v[0:1], s[46:47], 0, v[204:205]
	v_lshl_add_u64 v[2:3], v[2:3], 0, v[216:217]
	s_add_u32 s30, s30, s0
	v_readfirstlane_b32 s49, v191
	v_lshl_add_u64 v[0:1], v[0:1], 0, v[216:217]
	v_lshl_add_u64 v[2:3], v[2:3], 0, s[64:65]
	s_addc_u32 s31, s31, s1
	v_cndmask_b32_e64 v231, v3, v1, s[36:37]
	v_cndmask_b32_e64 v230, v2, v0, s[36:37]
	v_mov_b32_e32 v219, v193
	v_lshl_add_u64 v[2:3], s[12:13], 0, v[206:207]
	s_lshl_b32 s12, s49, 11
	s_add_i32 s13, 0, 0x8000
	v_lshl_add_u64 v[0:1], s[46:47], 0, v[208:209]
	v_lshl_add_u64 v[2:3], v[2:3], 0, v[218:219]
	s_cmp_lg_u32 s13, -1
	v_lshl_add_u64 v[0:1], v[0:1], 0, v[218:219]
	v_lshl_add_u64 v[2:3], v[2:3], 0, s[64:65]
	s_mul_i32 s65, s49, 0xc00
	s_cselect_b32 s13, s13, 0
	v_mov_b32_e32 v221, v193
	v_cndmask_b32_e64 v233, v3, v1, s[38:39]
	v_cndmask_b32_e64 v232, v2, v0, s[38:39]
	s_add_i32 s65, s65, s13
	v_lshl_add_u64 v[0:1], v[228:229], 0, v[220:221]
	v_mov_b32_e32 v223, v193
	s_add_i32 s66, s65, 0x6000
	s_mov_b32 s13, m0
	s_mov_b32 m0, s66
	s_nop 0
	global_load_lds_dwordx4 v[0:1], off
	s_mov_b32 m0, s13
	v_lshl_add_u64 v[0:1], v[230:231], 0, v[222:223]
	v_mov_b32_e32 v225, v193
	s_add_i32 s67, s65, 0x6400
	s_mov_b32 s13, m0
	s_mov_b32 m0, s67
	s_nop 0
	global_load_lds_dwordx4 v[0:1], off
	s_mov_b32 m0, s13
	v_lshl_add_u64 v[0:1], v[232:233], 0, v[224:225]
	s_add_i32 s68, s65, 0x6800
	s_mov_b32 s13, m0
	s_mov_b32 m0, s68
	s_nop 0
	global_load_lds_dwordx4 v[0:1], off
	s_mov_b32 m0, s13
	v_lshlrev_b32_e32 v0, 5, v191
	s_cmp_lg_u32 0, -1
	v_lshl_add_u32 v217, s48, 8, v0
	s_cselect_b32 s13, 0, 0
	v_or_b32_e32 v2, v217, v190
	v_mov_b64_e32 v[0:1], s[42:43]
	s_add_i32 s69, s12, s13
	s_mov_b32 s12, m0
	s_mov_b32 m0, s69
	s_nop 0
	global_load_lds_dwordx4 v211, s[30:31]
	s_mov_b32 m0, s12
	v_mov_b32_e32 v227, v193
	v_mad_i64_i32 v[0:1], s[12:13], v2, s77, v[0:1]
	s_add_i32 s70, s69, 0x400
	s_mov_b32 s12, m0
	s_mov_b32 m0, s70
	s_nop 0
	global_load_lds_dwordx4 v213, s[30:31]
	s_mov_b32 m0, s12
	v_lshl_add_u64 v[0:1], v[0:1], 0, v[226:227]
	global_load_dwordx4 v[186:189], v[0:1], off
	global_load_dwordx4 v[182:185], v[0:1], off offset:32
	global_load_dwordx4 v[178:181], v[0:1], off offset:64
	global_load_dwordx4 v[174:177], v[0:1], off offset:96
	global_load_dwordx4 v[170:173], v[0:1], off offset:128
	global_load_dwordx4 v[166:169], v[0:1], off offset:160
	global_load_dwordx4 v[162:165], v[0:1], off offset:192
	global_load_dwordx4 v[158:161], v[0:1], off offset:224
	global_load_dwordx4 v[154:157], v[0:1], off offset:256
	global_load_dwordx4 v[150:153], v[0:1], off offset:288
	global_load_dwordx4 v[146:149], v[0:1], off offset:320
	global_load_dwordx4 v[142:145], v[0:1], off offset:352
	s_waitcnt vmcnt(12)
	s_lshr_b32 s71, s62, 6
	s_waitcnt lgkmcnt(0)
	s_barrier
; #define WAITV(N) asm volatile("s_waitcnt vmcnt(" #N ")" ::: "memory")
; #define LBAR() asm volatile("s_waitcnt lgkmcnt(0)\n\ts_barrier" ::: "memory")
; __device__ __forceinline__ void attn_unit(const bf16_t* __restrict__ Qs, const bf16_t* __restrict__ Kn, const bf16_t* __restrict__ Kr, const bf16_t* __restrict__ Vs, bf16_t* Os, int q0, int Lp, char* lds, const int tid) {
;     ...
;     f32x16 pA0, pA1, pB0, pB1; float alA = 1.f, alB; bf16x8 pa[4]; s16x4 vl[4], vh[4]; const int NT = Lp / KVBLK;
;     static_assert(PADF >= KVBLK && PADF < 2 * KVBLK, "tile 0 fully masked, tile 1 partly");
;     ...
;     pA0 = f32x16{};
; #pragma unroll
;     for (int r = 0; r < 16; ++r) pA1[r] = -INFINITY;
;     WAITV(0); LBAR();
	s_add_i32 s72, s65, 0x400
	s_add_i32 s73, s65, 0x800
	s_add_i32 s64, s69, 0x4000
	s_add_i32 s63, s69, 0x4400
	v_mov_b32_e32 v14, v193
	v_mov_b32_e32 v15, v193
	s_add_u32 s42, s30, 0x80000
	v_mov_b32_e32 v0, v193
	v_mov_b32_e32 v1, v193
	v_mov_b32_e32 v2, v193
	v_mov_b32_e32 v3, v193
	v_mov_b32_e32 v4, v193
	v_mov_b32_e32 v5, v193
	v_mov_b32_e32 v6, v193
	v_mov_b32_e32 v7, v193
	v_mov_b32_e32 v8, v193
	v_mov_b32_e32 v9, v193
	v_mov_b32_e32 v10, v193
	v_mov_b32_e32 v11, v193
	v_mov_b32_e32 v12, v193
	v_mov_b32_e32 v13, v193
	s_waitcnt vmcnt(0) lgkmcnt(0)
	v_mov_b32_e32 v64, 0xff800000
	v_mov_b32_e32 v219, 0
	v_mov_b64_e32 v[62:63], v[14:15]
	v_mov_b64_e32 v[46:47], v[14:15]
	v_mov_b64_e32 v[30:31], v[14:15]
	s_addc_u32 s43, s31, 0
	v_mov_b32_e32 v221, 1.0
	v_mov_b32_e32 v130, 0xf149f2ca
	s_mov_b64 s[46:47], 2
	v_mov_b64_e32 v[60:61], v[12:13]
	v_mov_b64_e32 v[58:59], v[10:11]
	v_mov_b64_e32 v[56:57], v[8:9]
	v_mov_b64_e32 v[54:55], v[6:7]
	v_mov_b64_e32 v[52:53], v[4:5]
	v_mov_b64_e32 v[50:51], v[2:3]
	v_mov_b64_e32 v[48:49], v[0:1]
	v_mov_b64_e32 v[44:45], v[12:13]
	v_mov_b64_e32 v[42:43], v[10:11]
	v_mov_b64_e32 v[40:41], v[8:9]
	v_mov_b64_e32 v[38:39], v[6:7]
	v_mov_b64_e32 v[36:37], v[4:5]
	v_mov_b64_e32 v[34:35], v[2:3]
	v_mov_b64_e32 v[32:33], v[0:1]
	v_mov_b64_e32 v[28:29], v[12:13]
	v_mov_b64_e32 v[26:27], v[10:11]
	v_mov_b64_e32 v[24:25], v[8:9]
	v_mov_b64_e32 v[22:23], v[6:7]
	v_mov_b64_e32 v[20:21], v[4:5]
	v_mov_b64_e32 v[18:19], v[2:3]
	v_mov_b64_e32 v[16:17], v[0:1]
	v_mov_b32_e32 v94, 0
	v_mov_b32_e32 v95, v219
	v_mov_b32_e32 v96, v219
	v_mov_b32_e32 v97, v219
	v_mov_b32_e32 v98, v219
	v_mov_b32_e32 v99, v219
	v_mov_b32_e32 v100, v219
	v_mov_b32_e32 v101, v219
	v_mov_b32_e32 v102, v219
	v_mov_b32_e32 v103, v219
	v_mov_b32_e32 v104, v219
	v_mov_b32_e32 v105, v219
	v_mov_b32_e32 v106, v219
	v_mov_b32_e32 v107, v219
	v_mov_b32_e32 v108, v219
	v_mov_b32_e32 v109, v219
	v_mov_b32_e32 v65, v64
	v_mov_b32_e32 v66, v64
	v_mov_b32_e32 v67, v64
	v_mov_b32_e32 v68, v64
	v_mov_b32_e32 v69, v64
	v_mov_b32_e32 v70, v64
	v_mov_b32_e32 v71, v64
	v_mov_b32_e32 v72, v64
	v_mov_b32_e32 v73, v64
	v_mov_b32_e32 v74, v64
	v_mov_b32_e32 v75, v64
	v_mov_b32_e32 v76, v64
	v_mov_b32_e32 v77, v64
	v_mov_b32_e32 v78, v64
	v_mov_b32_e32 v79, v64
	.p2align 6
	s_branch .LBB0_622
